# stack6 plus rs-load hoist in the K|V projection tail GEMM epilogue
# baseline (speedup 1.0000x reference)
.LBB0_1530:
	ds_read_b128 v[150:153], v163
	ds_read_b128 v[154:157], v163 offset:1024
	ds_read_b128 v[158:161], v163 offset:2048
	ds_read_b128 v[168:171], v163 offset:3072
	ds_read_b128 v[172:175], v164
	ds_read_b128 v[176:179], v164 offset:1024
	ds_read_b128 v[180:183], v164 offset:2048
	ds_read_b128 v[184:187], v164 offset:3072
	s_add_u32 s30, s0, 0xfffc0080
	s_addc_u32 s31, s1, -1
	s_cmp_eq_u32 s60, 12
	s_cselect_b32 s35, s4, s31
	s_cselect_b32 s34, s21, s30
	s_cselect_b32 s31, s23, s59
	s_cselect_b32 s30, s25, s58
	v_lshl_add_u64 v[188:189], s[0:1], 0, v[142:143]
	s_add_i32 m0, s42, 0xc000
	ds_read_b128 v[192:195], v165
	ds_read_b128 v[196:199], v165 offset:1024
	ds_read_b128 v[200:203], v165 offset:2048
	ds_read_b128 v[204:207], v165 offset:3072
	ds_read_b128 v[208:211], v165 offset:4096
	ds_read_b128 v[212:215], v165 offset:5120
	ds_read_b128 v[216:219], v165 offset:6144
	ds_read_b128 v[220:223], v165 offset:7168
	global_load_lds_dwordx4 v[188:189], off
	v_lshl_add_u64 v[188:189], s[0:1], 0, v[140:141]
	s_add_i32 m0, s42, 0xe000
	s_nop 0
	global_load_lds_dwordx4 v[188:189], off
	s_waitcnt vmcnt(8)
	s_waitcnt lgkmcnt(0)
	s_barrier
	s_setprio 1
	s_waitcnt lgkmcnt(0)
	v_mfma_f32_16x16x32_bf16 v[124:127], v[150:153], v[192:195], v[124:127]
	v_mfma_f32_16x16x32_bf16 v[120:123], v[158:161], v[192:195], v[120:123]
	v_mfma_f32_16x16x32_bf16 v[108:111], v[150:153], v[200:203], v[108:111]
	v_mfma_f32_16x16x32_bf16 v[104:107], v[158:161], v[200:203], v[104:107]
	v_mfma_f32_16x16x32_bf16 v[92:95], v[150:153], v[208:211], v[92:95]
	v_mfma_f32_16x16x32_bf16 v[88:91], v[158:161], v[208:211], v[88:91]
	v_mfma_f32_16x16x32_bf16 v[76:79], v[150:153], v[216:219], v[76:79]
	v_mfma_f32_16x16x32_bf16 v[72:75], v[158:161], v[216:219], v[72:75]
	v_mfma_f32_16x16x32_bf16 v[124:127], v[154:157], v[196:199], v[124:127]
	v_mfma_f32_16x16x32_bf16 v[120:123], v[168:171], v[196:199], v[120:123]
	v_mfma_f32_16x16x32_bf16 v[108:111], v[154:157], v[204:207], v[108:111]
	v_mfma_f32_16x16x32_bf16 v[104:107], v[168:171], v[204:207], v[104:107]
	v_mfma_f32_16x16x32_bf16 v[92:95], v[154:157], v[212:215], v[92:95]
	v_mfma_f32_16x16x32_bf16 v[88:91], v[168:171], v[212:215], v[88:91]
	v_mfma_f32_16x16x32_bf16 v[76:79], v[154:157], v[220:223], v[76:79]
	v_mfma_f32_16x16x32_bf16 v[72:75], v[168:171], v[220:223], v[72:75]
	s_setprio 0
	s_setprio 1
	v_mfma_f32_16x16x32_bf16 v[116:119], v[172:175], v[192:195], v[116:119]
	v_mfma_f32_16x16x32_bf16 v[112:115], v[180:183], v[192:195], v[112:115]
	v_mfma_f32_16x16x32_bf16 v[100:103], v[172:175], v[200:203], v[100:103]
	v_mfma_f32_16x16x32_bf16 v[96:99], v[180:183], v[200:203], v[96:99]
	v_mfma_f32_16x16x32_bf16 v[84:87], v[172:175], v[208:211], v[84:87]
	v_mfma_f32_16x16x32_bf16 v[80:83], v[180:183], v[208:211], v[80:83]
	v_mfma_f32_16x16x32_bf16 v[68:71], v[172:175], v[216:219], v[68:71]
	v_mfma_f32_16x16x32_bf16 v[64:67], v[180:183], v[216:219], v[64:67]
	v_mfma_f32_16x16x32_bf16 v[116:119], v[176:179], v[196:199], v[116:119]
	v_mfma_f32_16x16x32_bf16 v[112:115], v[184:187], v[196:199], v[112:115]
	v_mfma_f32_16x16x32_bf16 v[100:103], v[176:179], v[204:207], v[100:103]
	v_mfma_f32_16x16x32_bf16 v[96:99], v[184:187], v[204:207], v[96:99]
	v_mfma_f32_16x16x32_bf16 v[84:87], v[176:179], v[212:215], v[84:87]
	v_mfma_f32_16x16x32_bf16 v[80:83], v[184:187], v[212:215], v[80:83]
	v_mfma_f32_16x16x32_bf16 v[68:71], v[176:179], v[220:223], v[68:71]
	v_mfma_f32_16x16x32_bf16 v[64:67], v[184:187], v[220:223], v[64:67]
	s_setprio 0
	s_barrier
	s_add_i32 s61, s48, s41
	v_lshl_add_u64 v[188:189], s[30:31], 0, v[132:133]
	s_mov_b32 m0, s61
	ds_read_b128 v[192:195], v165 offset:16384
	ds_read_b128 v[196:199], v165 offset:17408
	ds_read_b128 v[200:203], v165 offset:18432
	ds_read_b128 v[204:207], v165 offset:19456
	ds_read_b128 v[208:211], v165 offset:20480
	ds_read_b128 v[212:215], v165 offset:21504
	ds_read_b128 v[216:219], v165 offset:22528
	ds_read_b128 v[220:223], v165 offset:23552
	global_load_lds_dwordx4 v[188:189], off
	s_add_i32 m0, s61, 0x2000
	s_add_u32 s62, s30, 0x40000
	v_lshl_add_u64 v[224:225], s[30:31], 0, v[128:129]
	s_addc_u32 s63, s31, 0
	s_add_i32 s61, s49, s41
	global_load_lds_dwordx4 v[224:225], off
	v_lshl_add_u64 v[226:227], s[62:63], 0, v[132:133]
	s_mov_b32 m0, s61
	v_lshl_add_u64 v[228:229], s[34:35], 0, v[130:131]
	global_load_lds_dwordx4 v[226:227], off
	v_lshl_add_u64 v[226:227], s[62:63], 0, v[128:129]
	s_add_i32 m0, s61, 0x2000
	s_nop 0
	global_load_lds_dwordx4 v[226:227], off
	v_lshl_add_u64 v[226:227], s[34:35], 0, v[134:135]
	s_mov_b32 m0, s42
	s_nop 0
	global_load_lds_dwordx4 v[226:227], off
	s_mov_b32 m0, s43
	s_nop 0
	global_load_lds_dwordx4 v[228:229], off
	s_waitcnt vmcnt(8)
	s_waitcnt lgkmcnt(0)
	s_barrier
	s_setprio 1
	s_waitcnt lgkmcnt(0)
	v_mfma_f32_16x16x32_bf16 v[60:63], v[150:153], v[192:195], v[60:63]
	v_mfma_f32_16x16x32_bf16 v[56:59], v[158:161], v[192:195], v[56:59]
	v_mfma_f32_16x16x32_bf16 v[44:47], v[150:153], v[200:203], v[44:47]
	v_mfma_f32_16x16x32_bf16 v[40:43], v[158:161], v[200:203], v[40:43]
	v_mfma_f32_16x16x32_bf16 v[28:31], v[150:153], v[208:211], v[28:31]
	v_mfma_f32_16x16x32_bf16 v[24:27], v[158:161], v[208:211], v[24:27]
	v_mfma_f32_16x16x32_bf16 v[12:15], v[150:153], v[216:219], v[12:15]
	v_mfma_f32_16x16x32_bf16 v[8:11], v[158:161], v[216:219], v[8:11]
	v_mfma_f32_16x16x32_bf16 v[60:63], v[154:157], v[196:199], v[60:63]
	v_mfma_f32_16x16x32_bf16 v[56:59], v[168:171], v[196:199], v[56:59]
	v_mfma_f32_16x16x32_bf16 v[44:47], v[154:157], v[204:207], v[44:47]
	v_mfma_f32_16x16x32_bf16 v[40:43], v[168:171], v[204:207], v[40:43]
	v_mfma_f32_16x16x32_bf16 v[28:31], v[154:157], v[212:215], v[28:31]
	v_mfma_f32_16x16x32_bf16 v[24:27], v[168:171], v[212:215], v[24:27]
	v_mfma_f32_16x16x32_bf16 v[12:15], v[154:157], v[220:223], v[12:15]
	v_mfma_f32_16x16x32_bf16 v[8:11], v[168:171], v[220:223], v[8:11]
	s_setprio 0
	s_setprio 1
	v_mfma_f32_16x16x32_bf16 v[52:55], v[172:175], v[192:195], v[52:55]
	v_mfma_f32_16x16x32_bf16 v[48:51], v[180:183], v[192:195], v[48:51]
	v_mfma_f32_16x16x32_bf16 v[36:39], v[172:175], v[200:203], v[36:39]
	v_mfma_f32_16x16x32_bf16 v[32:35], v[180:183], v[200:203], v[32:35]
	v_mfma_f32_16x16x32_bf16 v[20:23], v[172:175], v[208:211], v[20:23]
	v_mfma_f32_16x16x32_bf16 v[16:19], v[180:183], v[208:211], v[16:19]
	v_mfma_f32_16x16x32_bf16 v[4:7], v[172:175], v[216:219], v[4:7]
	v_mfma_f32_16x16x32_bf16 v[0:3], v[180:183], v[216:219], v[0:3]
	v_mfma_f32_16x16x32_bf16 v[52:55], v[176:179], v[196:199], v[52:55]
	v_mfma_f32_16x16x32_bf16 v[48:51], v[184:187], v[196:199], v[48:51]
	v_mfma_f32_16x16x32_bf16 v[36:39], v[176:179], v[204:207], v[36:39]
	v_mfma_f32_16x16x32_bf16 v[32:35], v[184:187], v[204:207], v[32:35]
	v_mfma_f32_16x16x32_bf16 v[20:23], v[176:179], v[212:215], v[20:23]
	v_mfma_f32_16x16x32_bf16 v[16:19], v[184:187], v[212:215], v[16:19]
	v_mfma_f32_16x16x32_bf16 v[4:7], v[176:179], v[220:223], v[4:7]
	v_mfma_f32_16x16x32_bf16 v[0:3], v[184:187], v[220:223], v[0:3]
	s_setprio 0
	s_barrier
	s_add_i32 s61, 0, 0x18000
	v_add_u32_e32 v136, s61, v162
	s_add_i32 s62, 0, 0x1c000
	ds_read_b128 v[150:153], v136
	ds_read_b128 v[154:157], v136 offset:1024
	ds_read_b128 v[158:161], v136 offset:2048
	ds_read_b128 v[168:171], v136 offset:3072
	v_add_u32_e32 v136, s62, v162
	ds_read_b128 v[172:175], v136
	ds_read_b128 v[176:179], v136 offset:1024
	ds_read_b128 v[180:183], v136 offset:2048
	ds_read_b128 v[184:187], v136 offset:3072
	s_add_u32 s34, s34, 0x40000
	s_addc_u32 s35, s35, 0
	s_mov_b32 m0, s44
	v_lshl_add_u64 v[230:231], s[34:35], 0, v[134:135]
	ds_read_b128 v[192:195], v165 offset:32768
	ds_read_b128 v[196:199], v165 offset:33792
	ds_read_b128 v[200:203], v165 offset:34816
	ds_read_b128 v[204:207], v165 offset:35840
	ds_read_b128 v[208:211], v165 offset:36864
	ds_read_b128 v[212:215], v165 offset:37888
	ds_read_b128 v[216:219], v165 offset:38912
	ds_read_b128 v[220:223], v165 offset:39936
	global_load_lds_dwordx4 v[230:231], off
	v_lshl_add_u64 v[230:231], s[34:35], 0, v[130:131]
	s_mov_b32 m0, s45
	s_nop 0
	global_load_lds_dwordx4 v[230:231], off
	s_waitcnt vmcnt(8)
	s_waitcnt lgkmcnt(0)
	s_barrier
	s_setprio 1
	s_waitcnt lgkmcnt(0)
	v_mfma_f32_16x16x32_bf16 v[124:127], v[150:153], v[192:195], v[124:127]
	v_mfma_f32_16x16x32_bf16 v[120:123], v[158:161], v[192:195], v[120:123]
	v_mfma_f32_16x16x32_bf16 v[108:111], v[150:153], v[200:203], v[108:111]
	v_mfma_f32_16x16x32_bf16 v[104:107], v[158:161], v[200:203], v[104:107]
	v_mfma_f32_16x16x32_bf16 v[92:95], v[150:153], v[208:211], v[92:95]
	v_mfma_f32_16x16x32_bf16 v[88:91], v[158:161], v[208:211], v[88:91]
	v_mfma_f32_16x16x32_bf16 v[76:79], v[150:153], v[216:219], v[76:79]
	v_mfma_f32_16x16x32_bf16 v[72:75], v[158:161], v[216:219], v[72:75]
	v_mfma_f32_16x16x32_bf16 v[124:127], v[154:157], v[196:199], v[124:127]
	v_mfma_f32_16x16x32_bf16 v[120:123], v[168:171], v[196:199], v[120:123]
	v_mfma_f32_16x16x32_bf16 v[108:111], v[154:157], v[204:207], v[108:111]
	v_mfma_f32_16x16x32_bf16 v[104:107], v[168:171], v[204:207], v[104:107]
	v_mfma_f32_16x16x32_bf16 v[92:95], v[154:157], v[212:215], v[92:95]
	v_mfma_f32_16x16x32_bf16 v[88:91], v[168:171], v[212:215], v[88:91]
	v_mfma_f32_16x16x32_bf16 v[76:79], v[154:157], v[220:223], v[76:79]
	v_mfma_f32_16x16x32_bf16 v[72:75], v[168:171], v[220:223], v[72:75]
	s_setprio 0
	s_setprio 1
	v_mfma_f32_16x16x32_bf16 v[116:119], v[172:175], v[192:195], v[116:119]
	v_mfma_f32_16x16x32_bf16 v[112:115], v[180:183], v[192:195], v[112:115]
	v_mfma_f32_16x16x32_bf16 v[100:103], v[172:175], v[200:203], v[100:103]
	v_mfma_f32_16x16x32_bf16 v[96:99], v[180:183], v[200:203], v[96:99]
	v_mfma_f32_16x16x32_bf16 v[84:87], v[172:175], v[208:211], v[84:87]
	v_mfma_f32_16x16x32_bf16 v[80:83], v[180:183], v[208:211], v[80:83]
	v_mfma_f32_16x16x32_bf16 v[68:71], v[172:175], v[216:219], v[68:71]
	v_mfma_f32_16x16x32_bf16 v[64:67], v[180:183], v[216:219], v[64:67]
	v_mfma_f32_16x16x32_bf16 v[116:119], v[176:179], v[196:199], v[116:119]
	v_mfma_f32_16x16x32_bf16 v[112:115], v[184:187], v[196:199], v[112:115]
	v_mfma_f32_16x16x32_bf16 v[100:103], v[176:179], v[204:207], v[100:103]
	v_mfma_f32_16x16x32_bf16 v[96:99], v[184:187], v[204:207], v[96:99]
	v_mfma_f32_16x16x32_bf16 v[84:87], v[176:179], v[212:215], v[84:87]
	v_mfma_f32_16x16x32_bf16 v[80:83], v[184:187], v[212:215], v[80:83]
	v_mfma_f32_16x16x32_bf16 v[68:71], v[176:179], v[220:223], v[68:71]
	v_mfma_f32_16x16x32_bf16 v[64:67], v[184:187], v[220:223], v[64:67]
	s_setprio 0
	s_barrier
	s_add_i32 s34, s61, s41
	v_lshl_add_u64 v[188:189], v[188:189], 0, s[16:17]
	s_mov_b32 m0, s34
	ds_read_b128 v[192:195], v165 offset:49152
	ds_read_b128 v[196:199], v165 offset:50176
	ds_read_b128 v[200:203], v165 offset:51200
	ds_read_b128 v[204:207], v165 offset:52224
	ds_read_b128 v[208:211], v165 offset:53248
	ds_read_b128 v[212:215], v165 offset:54272
	ds_read_b128 v[216:219], v165 offset:55296
	ds_read_b128 v[220:223], v165 offset:56320
	global_load_lds_dwordx4 v[188:189], off
	s_add_i32 m0, s34, 0x2000
	s_add_u32 s30, s30, 0x40080
	v_lshl_add_u64 v[188:189], v[224:225], 0, s[16:17]
	s_addc_u32 s31, s31, 0
	s_add_i32 s34, s62, s41
	global_load_lds_dwordx4 v[188:189], off
	v_lshl_add_u64 v[188:189], s[30:31], 0, v[132:133]
	s_mov_b32 m0, s34
	s_nop 0
	global_load_lds_dwordx4 v[188:189], off
	v_lshl_add_u64 v[188:189], s[30:31], 0, v[128:129]
	s_add_i32 m0, s34, 0x2000
	s_nop 0
	global_load_lds_dwordx4 v[188:189], off
	v_lshl_add_u64 v[188:189], v[226:227], 0, s[16:17]
	s_mov_b32 m0, s46
	s_nop 0
	global_load_lds_dwordx4 v[188:189], off
	v_lshl_add_u64 v[188:189], v[228:229], 0, s[16:17]
	s_mov_b32 m0, s47
	s_nop 0
	global_load_lds_dwordx4 v[188:189], off
	s_waitcnt vmcnt(8)
	s_waitcnt lgkmcnt(0)
	s_barrier
	s_setprio 1
	s_waitcnt lgkmcnt(0)
	v_mfma_f32_16x16x32_bf16 v[60:63], v[150:153], v[192:195], v[60:63]
	v_mfma_f32_16x16x32_bf16 v[56:59], v[158:161], v[192:195], v[56:59]
	v_mfma_f32_16x16x32_bf16 v[44:47], v[150:153], v[200:203], v[44:47]
	v_mfma_f32_16x16x32_bf16 v[40:43], v[158:161], v[200:203], v[40:43]
	v_mfma_f32_16x16x32_bf16 v[28:31], v[150:153], v[208:211], v[28:31]
	v_mfma_f32_16x16x32_bf16 v[24:27], v[158:161], v[208:211], v[24:27]
	v_mfma_f32_16x16x32_bf16 v[12:15], v[150:153], v[216:219], v[12:15]
	v_mfma_f32_16x16x32_bf16 v[8:11], v[158:161], v[216:219], v[8:11]
	v_mfma_f32_16x16x32_bf16 v[60:63], v[154:157], v[196:199], v[60:63]
	v_mfma_f32_16x16x32_bf16 v[56:59], v[168:171], v[196:199], v[56:59]
	v_mfma_f32_16x16x32_bf16 v[44:47], v[154:157], v[204:207], v[44:47]
	v_mfma_f32_16x16x32_bf16 v[40:43], v[168:171], v[204:207], v[40:43]
	v_mfma_f32_16x16x32_bf16 v[28:31], v[154:157], v[212:215], v[28:31]
	v_mfma_f32_16x16x32_bf16 v[24:27], v[168:171], v[212:215], v[24:27]
	v_mfma_f32_16x16x32_bf16 v[12:15], v[154:157], v[220:223], v[12:15]
	v_mfma_f32_16x16x32_bf16 v[8:11], v[168:171], v[220:223], v[8:11]
	s_setprio 0
	s_setprio 1
	v_mfma_f32_16x16x32_bf16 v[52:55], v[172:175], v[192:195], v[52:55]
	v_mfma_f32_16x16x32_bf16 v[48:51], v[180:183], v[192:195], v[48:51]
	v_mfma_f32_16x16x32_bf16 v[36:39], v[172:175], v[200:203], v[36:39]
	v_mfma_f32_16x16x32_bf16 v[32:35], v[180:183], v[200:203], v[32:35]
	v_mfma_f32_16x16x32_bf16 v[20:23], v[172:175], v[208:211], v[20:23]
	v_mfma_f32_16x16x32_bf16 v[16:19], v[180:183], v[208:211], v[16:19]
	v_mfma_f32_16x16x32_bf16 v[4:7], v[172:175], v[216:219], v[4:7]
	v_mfma_f32_16x16x32_bf16 v[0:3], v[180:183], v[216:219], v[0:3]
	v_mfma_f32_16x16x32_bf16 v[52:55], v[176:179], v[196:199], v[52:55]
	v_mfma_f32_16x16x32_bf16 v[48:51], v[184:187], v[196:199], v[48:51]
	v_mfma_f32_16x16x32_bf16 v[36:39], v[176:179], v[204:207], v[36:39]
	v_mfma_f32_16x16x32_bf16 v[32:35], v[184:187], v[204:207], v[32:35]
	v_mfma_f32_16x16x32_bf16 v[20:23], v[176:179], v[212:215], v[20:23]
	v_mfma_f32_16x16x32_bf16 v[16:19], v[184:187], v[212:215], v[16:19]
	v_mfma_f32_16x16x32_bf16 v[4:7], v[176:179], v[220:223], v[4:7]
	v_mfma_f32_16x16x32_bf16 v[0:3], v[184:187], v[220:223], v[0:3]
	s_setprio 0
	s_barrier
	s_add_i32 s60, s60, 2
	s_add_u32 s58, s58, 0x100
	s_addc_u32 s59, s59, 0
	s_add_u32 s0, s0, 0x100
	s_addc_u32 s1, s1, 0
	s_cmp_gt_u32 s60, 13
	s_cbranch_scc0 .LBB0_1530
	v_lshl_add_u32 v210, s57, 8, v139
	v_ashrrev_i32_e32 v211, 31, v210
	v_lshl_add_u64 v[208:209], v[210:211], 2, s[14:15]
	global_load_dword v200, v[208:209], off
	global_load_dword v201, v[208:209], off offset:64
	global_load_dword v202, v[208:209], off offset:128
	global_load_dword v203, v[208:209], off offset:192
	global_load_dword v204, v[208:209], off offset:512
	global_load_dword v205, v[208:209], off offset:576
	global_load_dword v206, v[208:209], off offset:640
	global_load_dword v207, v[208:209], off offset:704
	s_and_b64 vcc, exec, s[18:19]
	s_cbranch_vccz .LBB0_1533
	s_barrier

.LBB0_1537:
	s_nop 0
	v_lshl_add_u64 v[160:161], v[156:157], 2, s[14:15]
	s_cmpk_gt_i32 s57, 0xff
	v_lshl_add_u64 v[168:169], v[154:155], 2, s[14:15]
	s_cselect_b32 s0, s52, 0x4948000
	s_cselect_b32 s1, s53, 0x5948000
	s_cselect_b32 s21, s54, 0x30f00000
	s_cselect_b32 s23, s55, 0x32f00000
	s_cselect_b32 s4, 0xffff0000, 0
	s_cmp_eq_u32 s33, 0
	s_cselect_b32 s0, s0, s1
	s_cselect_b32 s21, s21, s23
	s_lshl_b32 s0, s0, 2
	v_add_u32_e32 v156, s4, v156
	s_add_u32 s30, s10, s0
	v_ashrrev_i32_e32 v157, 31, v156
	s_addc_u32 s31, s11, 0
	v_lshlrev_b64 v[170:171], 10, v[156:157]
	s_add_u32 s0, s8, s21
	v_lshlrev_b32_e32 v136, 2, v138
	v_lshlrev_b64 v[172:173], 9, v[156:157]
	v_lshl_add_u64 v[170:171], s[30:31], 0, v[170:171]
	s_addc_u32 s1, s9, 0
	v_lshlrev_b32_e32 v158, 1, v138
	v_mov_b32_e32 v159, v137
	v_lshl_add_u64 v[170:171], v[170:171], 0, v[136:137]
	v_lshl_add_u64 v[172:173], s[0:1], 0, v[172:173]
	v_lshl_add_u64 v[172:173], v[172:173], 0, v[158:159]
	s_waitcnt vmcnt(0) lgkmcnt(0)
	v_fmamk_f32 v149, v200, 0x3a800000, v166
	v_mul_f32_e32 v155, 0x4b800000, v149
	v_cmp_gt_f32_e32 vcc, s50, v149
	s_nop 1
	v_cndmask_b32_e32 v149, v149, v155, vcc
	v_rsq_f32_e32 v149, v149
	s_nop 0
	v_mul_f32_e32 v155, 0x45800000, v149
	v_cndmask_b32_e32 v174, v149, v155, vcc
	v_pk_mul_f32 v[126:127], v[126:127], v[174:175] op_sel_hi:[1,0]
	v_pk_mul_f32 v[124:125], v[124:125], v[174:175] op_sel_hi:[1,0]
	v_pk_mul_f32 v[122:123], v[122:123], v[174:175] op_sel_hi:[1,0]
	v_pk_mul_f32 v[120:121], v[120:121], v[174:175] op_sel_hi:[1,0]
	v_pk_mul_f32 v[118:119], v[118:119], v[174:175] op_sel_hi:[1,0]
	v_pk_mul_f32 v[116:117], v[116:117], v[174:175] op_sel_hi:[1,0]
	v_pk_mul_f32 v[114:115], v[114:115], v[174:175] op_sel_hi:[1,0]
	v_pk_mul_f32 v[112:113], v[112:113], v[174:175] op_sel_hi:[1,0]
	global_store_dwordx4 v[170:171], v[124:127], off
	global_store_dwordx4 v[170:171], v[120:123], off offset:16
	s_nop 0
	v_cvt_pk_bf16_f32 v124, v124, v125
	v_cvt_pk_bf16_f32 v125, v126, v127
	v_cvt_pk_bf16_f32 v126, v120, v121
	v_cvt_pk_bf16_f32 v127, v122, v123
	v_cvt_pk_bf16_f32 v120, v116, v117
	v_cvt_pk_bf16_f32 v121, v118, v119
	v_cvt_pk_bf16_f32 v122, v112, v113
	v_cvt_pk_bf16_f32 v123, v114, v115
	global_store_dwordx4 v[172:173], v[124:127], off
	global_store_dwordx4 v[170:171], v[116:119], off offset:512
	global_store_dwordx4 v[170:171], v[112:115], off offset:528
	global_store_dwordx4 v[172:173], v[120:123], off offset:256
	s_nop 1
	v_add_u32_e32 v114, s4, v154
	v_ashrrev_i32_e32 v115, 31, v114
	v_lshlrev_b64 v[116:117], 10, v[114:115]
	v_lshlrev_b64 v[114:115], 9, v[114:115]
	v_lshl_add_u64 v[116:117], s[30:31], 0, v[116:117]
	v_lshl_add_u64 v[116:117], v[116:117], 0, v[136:137]
	v_lshl_add_u64 v[114:115], s[0:1], 0, v[114:115]
	v_lshl_add_u64 v[114:115], v[114:115], 0, v[158:159]
	v_lshl_add_u64 v[112:113], v[152:153], 2, s[14:15]
	v_fmamk_f32 v118, v201, 0x3a800000, v166
	v_mul_f32_e32 v119, 0x4b800000, v118
	v_cmp_gt_f32_e32 vcc, s50, v118
	s_nop 1
	v_cndmask_b32_e32 v118, v118, v119, vcc
	v_rsq_f32_e32 v118, v118
	s_nop 0
	v_mul_f32_e32 v119, 0x45800000, v118
	v_cndmask_b32_e32 v118, v118, v119, vcc
	v_pk_mul_f32 v[110:111], v[110:111], v[118:119] op_sel_hi:[1,0]
	v_pk_mul_f32 v[108:109], v[108:109], v[118:119] op_sel_hi:[1,0]
	v_pk_mul_f32 v[106:107], v[106:107], v[118:119] op_sel_hi:[1,0]
	v_pk_mul_f32 v[104:105], v[104:105], v[118:119] op_sel_hi:[1,0]
	v_pk_mul_f32 v[102:103], v[102:103], v[118:119] op_sel_hi:[1,0]
	v_pk_mul_f32 v[100:101], v[100:101], v[118:119] op_sel_hi:[1,0]
	v_pk_mul_f32 v[98:99], v[98:99], v[118:119] op_sel_hi:[1,0]
	v_pk_mul_f32 v[96:97], v[96:97], v[118:119] op_sel_hi:[1,0]
	global_store_dwordx4 v[116:117], v[108:111], off
	global_store_dwordx4 v[116:117], v[104:107], off offset:16
	s_nop 0
	v_cvt_pk_bf16_f32 v108, v108, v109
	v_cvt_pk_bf16_f32 v109, v110, v111
	v_cvt_pk_bf16_f32 v110, v104, v105
	v_cvt_pk_bf16_f32 v111, v106, v107
	v_cvt_pk_bf16_f32 v104, v100, v101
	v_cvt_pk_bf16_f32 v105, v102, v103
	v_cvt_pk_bf16_f32 v106, v96, v97
	v_cvt_pk_bf16_f32 v107, v98, v99
	global_store_dwordx4 v[114:115], v[108:111], off
	global_store_dwordx4 v[116:117], v[100:103], off offset:512
	global_store_dwordx4 v[116:117], v[96:99], off offset:528
	global_store_dwordx4 v[114:115], v[104:107], off offset:256
	s_nop 1
	v_add_u32_e32 v98, s4, v152
	v_ashrrev_i32_e32 v99, 31, v98
	v_lshlrev_b64 v[100:101], 10, v[98:99]
	v_lshlrev_b64 v[98:99], 9, v[98:99]
	v_lshl_add_u64 v[100:101], s[30:31], 0, v[100:101]
	v_lshl_add_u64 v[100:101], v[100:101], 0, v[136:137]
	v_lshl_add_u64 v[98:99], s[0:1], 0, v[98:99]
	v_lshl_add_u64 v[98:99], v[98:99], 0, v[158:159]
	v_lshl_add_u64 v[96:97], v[150:151], 2, s[14:15]
	v_fmamk_f32 v102, v202, 0x3a800000, v166
	v_mul_f32_e32 v103, 0x4b800000, v102
	v_cmp_gt_f32_e32 vcc, s50, v102
	s_nop 1
	v_cndmask_b32_e32 v102, v102, v103, vcc
	v_rsq_f32_e32 v102, v102
	s_nop 0
	v_mul_f32_e32 v103, 0x45800000, v102
	v_cndmask_b32_e32 v102, v102, v103, vcc
	v_pk_mul_f32 v[94:95], v[94:95], v[102:103] op_sel_hi:[1,0]
	v_pk_mul_f32 v[92:93], v[92:93], v[102:103] op_sel_hi:[1,0]
	v_pk_mul_f32 v[90:91], v[90:91], v[102:103] op_sel_hi:[1,0]
	v_pk_mul_f32 v[88:89], v[88:89], v[102:103] op_sel_hi:[1,0]
	v_pk_mul_f32 v[86:87], v[86:87], v[102:103] op_sel_hi:[1,0]
	v_pk_mul_f32 v[84:85], v[84:85], v[102:103] op_sel_hi:[1,0]
	v_pk_mul_f32 v[82:83], v[82:83], v[102:103] op_sel_hi:[1,0]
	v_pk_mul_f32 v[80:81], v[80:81], v[102:103] op_sel_hi:[1,0]
	global_store_dwordx4 v[100:101], v[92:95], off
	global_store_dwordx4 v[100:101], v[88:91], off offset:16
	s_nop 0
	v_cvt_pk_bf16_f32 v92, v92, v93
	v_cvt_pk_bf16_f32 v93, v94, v95
	v_cvt_pk_bf16_f32 v94, v88, v89
	v_cvt_pk_bf16_f32 v95, v90, v91
	v_cvt_pk_bf16_f32 v88, v84, v85
	v_cvt_pk_bf16_f32 v89, v86, v87
	v_cvt_pk_bf16_f32 v90, v80, v81
	v_cvt_pk_bf16_f32 v91, v82, v83
	global_store_dwordx4 v[98:99], v[92:95], off
	global_store_dwordx4 v[100:101], v[84:87], off offset:512
	global_store_dwordx4 v[100:101], v[80:83], off offset:528
	global_store_dwordx4 v[98:99], v[88:91], off offset:256
	s_nop 1
	v_add_u32_e32 v80, s4, v150
	v_ashrrev_i32_e32 v81, 31, v80
	v_lshlrev_b64 v[82:83], 10, v[80:81]
	v_lshlrev_b64 v[80:81], 9, v[80:81]
	v_lshl_add_u64 v[82:83], s[30:31], 0, v[82:83]
	v_lshl_add_u64 v[82:83], v[82:83], 0, v[136:137]
	v_lshl_add_u64 v[80:81], s[0:1], 0, v[80:81]
	v_lshl_add_u64 v[80:81], v[80:81], 0, v[158:159]
	v_fmamk_f32 v84, v203, 0x3a800000, v166
	v_mul_f32_e32 v85, 0x4b800000, v84
	v_cmp_gt_f32_e32 vcc, s50, v84
	s_nop 1
	v_cndmask_b32_e32 v84, v84, v85, vcc
	v_rsq_f32_e32 v84, v84
	s_nop 0
	v_mul_f32_e32 v85, 0x45800000, v84
	v_cndmask_b32_e32 v84, v84, v85, vcc
	v_pk_mul_f32 v[78:79], v[78:79], v[84:85] op_sel_hi:[1,0]
	v_pk_mul_f32 v[76:77], v[76:77], v[84:85] op_sel_hi:[1,0]
	v_pk_mul_f32 v[74:75], v[74:75], v[84:85] op_sel_hi:[1,0]
	v_pk_mul_f32 v[72:73], v[72:73], v[84:85] op_sel_hi:[1,0]
	v_pk_mul_f32 v[70:71], v[70:71], v[84:85] op_sel_hi:[1,0]
	v_pk_mul_f32 v[68:69], v[68:69], v[84:85] op_sel_hi:[1,0]
	v_pk_mul_f32 v[66:67], v[66:67], v[84:85] op_sel_hi:[1,0]
	v_pk_mul_f32 v[64:65], v[64:65], v[84:85] op_sel_hi:[1,0]
	global_store_dwordx4 v[82:83], v[76:79], off
	global_store_dwordx4 v[82:83], v[72:75], off offset:16
	s_nop 0
	v_cvt_pk_bf16_f32 v76, v76, v77
	v_cvt_pk_bf16_f32 v77, v78, v79
	v_cvt_pk_bf16_f32 v78, v72, v73
	v_cvt_pk_bf16_f32 v79, v74, v75
	v_cvt_pk_bf16_f32 v72, v68, v69
	v_cvt_pk_bf16_f32 v73, v70, v71
	v_cvt_pk_bf16_f32 v74, v64, v65
	v_cvt_pk_bf16_f32 v75, v66, v67
	global_store_dwordx4 v[80:81], v[76:79], off
	global_store_dwordx4 v[82:83], v[68:71], off offset:512
	global_store_dwordx4 v[82:83], v[64:67], off offset:528
	global_store_dwordx4 v[80:81], v[72:75], off offset:256
	s_nop 1
	v_add_u32_e32 v64, 0x80, v156
	v_ashrrev_i32_e32 v65, 31, v64
	v_lshlrev_b64 v[66:67], 10, v[64:65]
	v_lshlrev_b64 v[64:65], 9, v[64:65]
	v_lshl_add_u64 v[66:67], s[30:31], 0, v[66:67]
	v_lshl_add_u64 v[66:67], v[66:67], 0, v[136:137]
	v_lshl_add_u64 v[64:65], s[0:1], 0, v[64:65]
	v_lshl_add_u64 v[64:65], v[64:65], 0, v[158:159]
	v_fmamk_f32 v68, v204, 0x3a800000, v166
	v_mul_f32_e32 v69, 0x4b800000, v68
	v_cmp_gt_f32_e32 vcc, s50, v68
	s_nop 1
	v_cndmask_b32_e32 v68, v68, v69, vcc
	v_rsq_f32_e32 v68, v68
	s_nop 0
	v_mul_f32_e32 v69, 0x45800000, v68
	v_cndmask_b32_e32 v68, v68, v69, vcc
	v_pk_mul_f32 v[62:63], v[62:63], v[68:69] op_sel_hi:[1,0]
	v_pk_mul_f32 v[60:61], v[60:61], v[68:69] op_sel_hi:[1,0]
	v_pk_mul_f32 v[58:59], v[58:59], v[68:69] op_sel_hi:[1,0]
	v_pk_mul_f32 v[56:57], v[56:57], v[68:69] op_sel_hi:[1,0]
	v_pk_mul_f32 v[54:55], v[54:55], v[68:69] op_sel_hi:[1,0]
	v_pk_mul_f32 v[52:53], v[52:53], v[68:69] op_sel_hi:[1,0]
	v_pk_mul_f32 v[50:51], v[50:51], v[68:69] op_sel_hi:[1,0]
	v_pk_mul_f32 v[48:49], v[48:49], v[68:69] op_sel_hi:[1,0]
	global_store_dwordx4 v[66:67], v[60:63], off
	global_store_dwordx4 v[66:67], v[56:59], off offset:16
	s_nop 0
	v_cvt_pk_bf16_f32 v60, v60, v61
	v_cvt_pk_bf16_f32 v61, v62, v63
	v_cvt_pk_bf16_f32 v62, v56, v57
	v_cvt_pk_bf16_f32 v63, v58, v59
	v_cvt_pk_bf16_f32 v56, v52, v53
	v_cvt_pk_bf16_f32 v57, v54, v55
	v_cvt_pk_bf16_f32 v58, v48, v49
	v_cvt_pk_bf16_f32 v59, v50, v51
	global_store_dwordx4 v[64:65], v[60:63], off
	global_store_dwordx4 v[66:67], v[52:55], off offset:512
	global_store_dwordx4 v[66:67], v[48:51], off offset:528
	global_store_dwordx4 v[64:65], v[56:59], off offset:256
	s_nop 1
	v_add_u32_e32 v48, 0x90, v156
	v_ashrrev_i32_e32 v49, 31, v48
	v_lshlrev_b64 v[50:51], 10, v[48:49]
	v_lshlrev_b64 v[48:49], 9, v[48:49]
	v_lshl_add_u64 v[50:51], s[30:31], 0, v[50:51]
	v_lshl_add_u64 v[50:51], v[50:51], 0, v[136:137]
	v_lshl_add_u64 v[48:49], s[0:1], 0, v[48:49]
	v_lshl_add_u64 v[48:49], v[48:49], 0, v[158:159]
	v_fmamk_f32 v52, v205, 0x3a800000, v166
	v_mul_f32_e32 v53, 0x4b800000, v52
	v_cmp_gt_f32_e32 vcc, s50, v52
	s_nop 1
	v_cndmask_b32_e32 v52, v52, v53, vcc
	v_rsq_f32_e32 v52, v52
	s_nop 0
	v_mul_f32_e32 v53, 0x45800000, v52
	v_cndmask_b32_e32 v52, v52, v53, vcc
	v_pk_mul_f32 v[46:47], v[46:47], v[52:53] op_sel_hi:[1,0]
	v_pk_mul_f32 v[44:45], v[44:45], v[52:53] op_sel_hi:[1,0]
	v_pk_mul_f32 v[42:43], v[42:43], v[52:53] op_sel_hi:[1,0]
	v_pk_mul_f32 v[40:41], v[40:41], v[52:53] op_sel_hi:[1,0]
	v_pk_mul_f32 v[38:39], v[38:39], v[52:53] op_sel_hi:[1,0]
	v_pk_mul_f32 v[36:37], v[36:37], v[52:53] op_sel_hi:[1,0]
	v_pk_mul_f32 v[34:35], v[34:35], v[52:53] op_sel_hi:[1,0]
	v_pk_mul_f32 v[32:33], v[32:33], v[52:53] op_sel_hi:[1,0]
	global_store_dwordx4 v[50:51], v[44:47], off
	global_store_dwordx4 v[50:51], v[40:43], off offset:16
	s_nop 0
	v_cvt_pk_bf16_f32 v44, v44, v45
	v_cvt_pk_bf16_f32 v45, v46, v47
	v_cvt_pk_bf16_f32 v46, v40, v41
	v_cvt_pk_bf16_f32 v47, v42, v43
	v_cvt_pk_bf16_f32 v40, v36, v37
	v_cvt_pk_bf16_f32 v41, v38, v39
	v_cvt_pk_bf16_f32 v42, v32, v33
	v_cvt_pk_bf16_f32 v43, v34, v35
	global_store_dwordx4 v[48:49], v[44:47], off
	global_store_dwordx4 v[50:51], v[36:39], off offset:512
	global_store_dwordx4 v[50:51], v[32:35], off offset:528
	global_store_dwordx4 v[48:49], v[40:43], off offset:256
	s_nop 1
	v_add_u32_e32 v32, 0xa0, v156
	v_ashrrev_i32_e32 v33, 31, v32
	v_lshlrev_b64 v[34:35], 10, v[32:33]
	v_lshlrev_b64 v[32:33], 9, v[32:33]
	v_lshl_add_u64 v[34:35], s[30:31], 0, v[34:35]
	v_lshl_add_u64 v[34:35], v[34:35], 0, v[136:137]
	v_lshl_add_u64 v[32:33], s[0:1], 0, v[32:33]
	v_lshl_add_u64 v[32:33], v[32:33], 0, v[158:159]
	v_fmamk_f32 v36, v206, 0x3a800000, v166
	v_mul_f32_e32 v37, 0x4b800000, v36
	v_cmp_gt_f32_e32 vcc, s50, v36
	s_nop 1
	v_cndmask_b32_e32 v36, v36, v37, vcc
	v_rsq_f32_e32 v36, v36
	s_nop 0
	v_mul_f32_e32 v37, 0x45800000, v36
	v_cndmask_b32_e32 v36, v36, v37, vcc
	v_pk_mul_f32 v[30:31], v[30:31], v[36:37] op_sel_hi:[1,0]
	v_pk_mul_f32 v[28:29], v[28:29], v[36:37] op_sel_hi:[1,0]
	v_pk_mul_f32 v[26:27], v[26:27], v[36:37] op_sel_hi:[1,0]
	v_pk_mul_f32 v[24:25], v[24:25], v[36:37] op_sel_hi:[1,0]
	v_pk_mul_f32 v[22:23], v[22:23], v[36:37] op_sel_hi:[1,0]
	v_pk_mul_f32 v[20:21], v[20:21], v[36:37] op_sel_hi:[1,0]
	v_pk_mul_f32 v[18:19], v[18:19], v[36:37] op_sel_hi:[1,0]
	v_pk_mul_f32 v[16:17], v[16:17], v[36:37] op_sel_hi:[1,0]
	global_store_dwordx4 v[34:35], v[28:31], off
	global_store_dwordx4 v[34:35], v[24:27], off offset:16
	s_nop 0
	v_cvt_pk_bf16_f32 v28, v28, v29
	v_cvt_pk_bf16_f32 v29, v30, v31
	v_cvt_pk_bf16_f32 v30, v24, v25
	v_cvt_pk_bf16_f32 v31, v26, v27
	v_cvt_pk_bf16_f32 v24, v20, v21
	v_cvt_pk_bf16_f32 v25, v22, v23
	v_cvt_pk_bf16_f32 v26, v16, v17
	v_cvt_pk_bf16_f32 v27, v18, v19
	global_store_dwordx4 v[32:33], v[28:31], off
	global_store_dwordx4 v[34:35], v[20:23], off offset:512
	global_store_dwordx4 v[34:35], v[16:19], off offset:528
	global_store_dwordx4 v[32:33], v[24:27], off offset:256
	s_nop 1
	v_add_u32_e32 v16, 0xb0, v156
	v_ashrrev_i32_e32 v17, 31, v16
	v_lshlrev_b64 v[18:19], 10, v[16:17]
	v_lshlrev_b64 v[16:17], 9, v[16:17]
	v_lshl_add_u64 v[18:19], s[30:31], 0, v[18:19]
	v_lshl_add_u64 v[18:19], v[18:19], 0, v[136:137]
	v_lshl_add_u64 v[16:17], s[0:1], 0, v[16:17]
	v_lshl_add_u64 v[16:17], v[16:17], 0, v[158:159]
	v_fmamk_f32 v20, v207, 0x3a800000, v166
	v_mul_f32_e32 v21, 0x4b800000, v20
	v_cmp_gt_f32_e32 vcc, s50, v20
	s_nop 1
	v_cndmask_b32_e32 v20, v20, v21, vcc
	v_rsq_f32_e32 v20, v20
	s_nop 0
	v_mul_f32_e32 v21, 0x45800000, v20
	v_cndmask_b32_e32 v20, v20, v21, vcc
	v_pk_mul_f32 v[14:15], v[14:15], v[20:21] op_sel_hi:[1,0]
	v_pk_mul_f32 v[12:13], v[12:13], v[20:21] op_sel_hi:[1,0]
	v_pk_mul_f32 v[10:11], v[10:11], v[20:21] op_sel_hi:[1,0]
	v_pk_mul_f32 v[8:9], v[8:9], v[20:21] op_sel_hi:[1,0]
	v_pk_mul_f32 v[6:7], v[6:7], v[20:21] op_sel_hi:[1,0]
	v_pk_mul_f32 v[4:5], v[4:5], v[20:21] op_sel_hi:[1,0]
	v_pk_mul_f32 v[2:3], v[2:3], v[20:21] op_sel_hi:[1,0]
	v_pk_mul_f32 v[0:1], v[0:1], v[20:21] op_sel_hi:[1,0]
	global_store_dwordx4 v[18:19], v[12:15], off
	global_store_dwordx4 v[18:19], v[8:11], off offset:16
	s_nop 0
	v_cvt_pk_bf16_f32 v12, v12, v13
	v_cvt_pk_bf16_f32 v13, v14, v15
	v_cvt_pk_bf16_f32 v14, v8, v9
	v_cvt_pk_bf16_f32 v15, v10, v11
	v_cvt_pk_bf16_f32 v8, v4, v5
	v_cvt_pk_bf16_f32 v9, v6, v7
	v_cvt_pk_bf16_f32 v10, v0, v1
	v_cvt_pk_bf16_f32 v11, v2, v3
	global_store_dwordx4 v[16:17], v[12:15], off
	global_store_dwordx4 v[18:19], v[4:7], off offset:512
	global_store_dwordx4 v[18:19], v[0:3], off offset:528
	global_store_dwordx4 v[16:17], v[8:11], off offset:256
	s_andn2_b64 vcc, exec, s[2:3]
	s_mov_b64 s[0:1], -1
	s_cbranch_vccnz .LBB0_1526
